# desync: half of the CUs (blockIdx bit 3) sleep ~6us at the start of each FFN in-projection phase
# speedup vs baseline: 1.0062x; 1.0062x over previous
; #define PG8_STAGE(bufoff, gbase, voff) do { _Pragma("unroll") for (int _i = 0; _i < 2; ++_i) \
;         __builtin_amdgcn_global_load_lds((const unsigned*)((const char*)(gbase) + (voff)[_i]), (PG8_LAS unsigned*)(lds + (bufoff) + ldsw + _i * 8192), 16, 0, 0); } while (0)
; #define PG8_WAIT_V(n) asm volatile("s_waitcnt vmcnt(" #n ")" ::: "memory")
; #define PG8_BAR __builtin_amdgcn_s_barrier()
; template <class Epi, class Sched, bool ALIGN_EPI = false, bool SP2 = false>
; __device__ __forceinline__ void gemm_phase(PG8_LAS unsigned char* lds, const Gemm g, const Sched& S, const Epi& E) {
;     ...
;     const int tid = tid_, wid = __builtin_amdgcn_readfirstlane(tid >> 6), lane = tid & 63, wr = wid >> 2, wc = wid & 3, fr = lane & 15, fq = lane >> 4;
;     const int K = g.K, nt = K / BK;
;     unsigned voffA[2], voffB[2];
; #pragma unroll
;     for (int i = 0; i < 2; ++i) { int R, C; stage_rc(tid * 16 + i * 8192, R, C); const int Rb = Epi::PERM ? ((R & ~31) + perm32(R & 31)) : R;
;         voffA[i] = (unsigned)(R * K + C) * 2u; voffB[i] = (unsigned)(Rb * K + C) * 2u; }
;     const size_t kstep = (size_t)(BK * 2);
;     const size_t hstep = (size_t)HALF * K * 2;
;     const size_t tstep = 2 * hstep;
;     const unsigned ldsw = (unsigned)wid * 1024u;
;     const int aoff = lds_byte(wr * 64 + fr, fq * 8), boff = lds_byte(wc * 32 + fr, fq * 8);
;     ...
;     Unit cur, nxt; int ui = 0;
;     if (!S.next(0, cur)) return;
;     f32x4 acc[2][2][4][2];
; #pragma unroll
;     for (int a = 0; a < 2; ++a)
; #pragma unroll
;         for (int b = 0; b < 2; ++b)
; #pragma unroll
;             for (int m = 0; m < 4; ++m)
; #pragma unroll
;                 for (int n = 0; n < 2; ++n) acc[a][b][m][n] = (f32x4){0.f, 0.f, 0.f, 0.f};
;     bf16x8 At[4][2], B0[2][2], B1[2][2];
;     const char* cA = (const char*)(cur.sw ? g.A2 : g.A) + (size_t)cur.pm * tstep; const char* cB = (const char*)(cur.sw ? g.Bt2 : g.Bt) + (size_t)cur.pn * tstep;
;     S.a_ready(cur);
;     if constexpr (SP2) {
;         PG8_STAGE(PG8_SB(0, 0), cB, voffB); PG8_STAGE(PG8_SB(0, 1), cB + hstep, voffB); PG8_STAGE(PG8_SA(0, 0), cA, voffA); PG8_STAGE(PG8_SA(0, 1), cA + hstep, voffA);
;         if (wr == 1) PG8_BAR;
;         PG8_WAIT_V(2); PG8_BAR;
;         PG8_STAGE(PG8_SB(1, 0), cB + kstep, voffB); PG8_STAGE(PG8_SA(1, 0), cA + kstep, voffA); PG8_STAGE(PG8_SB(1, 1), cB + hstep + kstep, voffB);
;         PG8_WAIT_V(6); PG8_BAR;
.LBB0_100:
	s_mul_i32 s4, s64, 0xab
	s_bfe_u32 s10, s4, 0x70009
	s_mul_i32 s4, s10, -3
	s_add_i32 s4, s4, s64
	s_cmp_lg_u32 s4, 1
	s_cselect_b64 s[6:7], -1, 0
	s_cmp_eq_u32 s4, 1
	v_writelane_b32 v248, s4, 32
	s_cselect_b64 s[8:9], -1, 0
	s_and_b64 vcc, exec, s[8:9]
	v_writelane_b32 v248, s64, 33
	v_writelane_b32 v248, s10, 34
	s_cbranch_vccnz .LBB0_119
	v_readlane_b32 s4, v250, 30
	v_mov_b32_e32 v0, v202
	v_readlane_b32 s5, v250, 31
	s_andn2_b64 vcc, exec, s[4:5]
	v_readfirstlane_b32 s4, v0
	s_cbranch_vccnz .LBB0_119
	s_bitcmp1_b32 s2, 3
	s_cbranch_scc0 .Lnodelay
	s_sleep 127
	s_sleep 60
.Lnodelay:
	v_readlane_b32 s5, v248, 32
	s_cmp_eq_u32 s5, 2
	s_mov_b32 s5, s10
	s_cselect_b64 s[10:11], -1, 0
	v_lshlrev_b32_e32 v4, 4, v0
	v_cndmask_b32_e64 v1, 0, 1, s[10:11]
	v_add_u32_e32 v2, 0x2000, v4
	v_readfirstlane_b32 s10, v1
	v_ashrrev_i32_e32 v1, 31, v2
	v_lshrrev_b32_e32 v1, 22, v1
	v_add_u32_e32 v1, v2, v1
	v_ashrrev_i32_e32 v1, 10, v1
	v_mul_i32_i24_e32 v3, 0x400, v1
	v_sub_u32_e32 v2, v2, v3
	v_lshrrev_b32_e32 v3, 4, v2
	v_bitop3_b32 v3, v3, v2, 32 bitop3:0x6c
	v_ashrrev_i32_e32 v2, 31, v3
	v_lshrrev_b32_e32 v2, 26, v2
	v_add_u32_e32 v5, v3, v2
	v_lshlrev_b32_e32 v6, 3, v1
	v_ashrrev_i32_e32 v2, 6, v5
	v_and_b32_e32 v6, -16, v6
	s_lshl_b32 s5, s5, 1
	v_add_u32_e32 v6, v2, v6
	s_or_b32 s5, s5, s10
	v_and_b32_e32 v7, 3, v2
	s_mov_b32 s10, 0x1fffe0
	v_lshrrev_b32_e32 v8, 2, v6
	v_lshlrev_b32_e32 v9, 1, v6
	v_and_b32_e32 v5, 0xc0, v5
	v_and_or_b32 v7, v6, s10, v7
	v_and_b32_e32 v8, 4, v8
	v_and_b32_e32 v9, 24, v9
	v_sub_u32_e32 v3, v3, v5
	v_or3_b32 v7, v7, v8, v9
	v_lshlrev_b32_e32 v8, 5, v1
	v_ashrrev_i16_sdwa v3, v206, sext(v3) dst_sel:DWORD dst_unused:UNUSED_PAD src0_sel:DWORD src1_sel:BYTE_0
	v_and_b32_e32 v8, 32, v8
	v_bfe_i32 v3, v3, 0, 16
	v_add_lshl_u32 v5, v8, v3, 1
	v_lshl_add_u32 v130, v7, 11, v5
	v_lshl_add_u32 v132, v6, 11, v5
	v_bfe_i32 v5, v0, 27, 1
	v_lshrrev_b32_e32 v5, 22, v5
	v_add_u32_e32 v5, v4, v5
	v_and_b32_e32 v5, 0xfffffc00, v5
	v_sub_u32_e32 v4, v4, v5
	v_lshrrev_b32_e32 v5, 4, v4
	v_bitop3_b32 v6, v5, v4, 32 bitop3:0x6c
	v_ashrrev_i32_e32 v5, 31, v0
	v_lshrrev_b32_e32 v5, 26, v5
	v_ashrrev_i32_e32 v4, 31, v6
	v_add_u32_e32 v5, v0, v5
	v_lshrrev_b32_e32 v4, 26, v4
	v_ashrrev_i32_e32 v5, 6, v5
	v_add_u32_e32 v7, v6, v4
	v_lshlrev_b32_e32 v8, 3, v5
	v_readlane_b32 s12, v250, 0
	v_ashrrev_i32_e32 v4, 6, v7
	v_and_b32_e32 v8, -16, v8
	s_mul_i32 s5, s5, 0xb00000
	v_readlane_b32 s14, v250, 2
	v_add_u32_e32 v8, v4, v8
	v_readlane_b32 s15, v250, 3
	s_add_u32 s20, s14, s5
	v_and_b32_e32 v9, 3, v4
	v_lshrrev_b32_e32 v10, 2, v8
	v_lshlrev_b32_e32 v11, 1, v8
	v_and_b32_e32 v7, 0xc0, v7
	s_addc_u32 s38, s15, 0
	s_ashr_i32 s5, s4, 6
	v_and_or_b32 v9, v8, s10, v9
	v_and_b32_e32 v10, 4, v10
	v_and_b32_e32 v11, 24, v11
	v_sub_u32_e32 v6, v6, v7
	s_ashr_i32 s12, s4, 8
	s_lshl_b32 s39, s5, 10
	v_or3_b32 v9, v9, v10, v11
	v_lshlrev_b32_e32 v10, 5, v5
	v_ashrrev_i16_sdwa v6, v206, sext(v6) dst_sel:DWORD dst_unused:UNUSED_PAD src0_sel:DWORD src1_sel:BYTE_0
	v_readlane_b32 s10, v249, 49
	v_and_b32_e32 v10, 32, v10
	v_bfe_i32 v6, v6, 0, 16
	v_readlane_b32 s11, v249, 50
	s_add_u32 s46, s20, s10
	v_add_lshl_u32 v7, v10, v6, 1
	s_addc_u32 s47, s38, s11
	s_add_i32 s50, s39, 0
	v_lshl_add_u32 v134, v9, 11, v7
	s_add_i32 m0, s50, 0x10000
	v_lshl_add_u32 v136, v8, 11, v7
	global_load_lds_dwordx4 v134, s[46:47]
	s_add_i32 m0, s50, 0x12000
	s_add_u32 s10, s46, 0x40000
	global_load_lds_dwordx4 v130, s[46:47]
	s_addc_u32 s11, s47, 0
	s_add_i32 m0, s50, 0x14000
	s_add_i32 s51, s50, 0x2000
	global_load_lds_dwordx4 v134, s[10:11]
	s_add_i32 m0, s50, 0x16000
	s_add_i32 s52, s50, 0x4000
	global_load_lds_dwordx4 v130, s[10:11]
	v_readlane_b32 s10, v249, 53
	s_mov_b32 m0, s50
	v_readlane_b32 s11, v249, 54
	s_add_i32 s53, s50, 0x6000
	s_cmp_eq_u32 s12, 1
	v_readlane_b32 s13, v250, 1
	s_nop 1
	global_load_lds_dwordx4 v136, s[10:11]
	s_mov_b32 m0, s51
	s_nop 0
	global_load_lds_dwordx4 v132, s[10:11]
	v_readlane_b32 s10, v249, 55
	s_mov_b32 m0, s52
	v_readlane_b32 s11, v249, 56
	s_nop 4
	global_load_lds_dwordx4 v136, s[10:11]
	s_mov_b32 m0, s53
	s_nop 0
	global_load_lds_dwordx4 v132, s[10:11]
	s_cselect_b64 s[10:11], -1, 0
	s_cmp_lg_u32 s12, 1
	s_cbranch_scc1 .LBB0_104
	s_barrier
.LBB0_104:
	v_mov_b32_e32 v135, v80
	v_lshl_add_u64 v[8:9], s[46:47], 0, v[134:135]
	v_mov_b32_e32 v131, v80
	v_readlane_b32 s44, v249, 53
	s_lshl_b32 s5, s5, 5
	v_lshl_add_u64 v[10:11], s[46:47], 0, v[130:131]
	v_mov_b32_e32 v137, v80
	v_readlane_b32 s45, v249, 54
	s_and_b32 s55, s5, 0x60
	s_add_i32 m0, s50, 0x18000
	v_lshl_add_u64 v[8:9], v[8:9], 0, s[40:41]
	v_lshl_add_u64 v[12:13], s[44:45], 0, v[136:137]
	v_mov_b32_e32 v133, v80
	s_lshl_b32 s54, s12, 6
	s_lshl_b32 s14, s12, 13
	s_lshl_b32 s5, s55, 7
	s_waitcnt vmcnt(2)
	s_barrier
	global_load_lds_dwordx4 v[8:9], off
	v_lshl_add_u64 v[8:9], v[10:11], 0, s[40:41]
	s_add_i32 m0, s50, 0x1a000
	s_add_i32 s56, s50, 0x8000
	s_add_i32 s57, s50, 0xa000
	v_lshl_add_u64 v[14:15], s[44:45], 0, v[132:133]
	global_load_lds_dwordx4 v[8:9], off
	v_lshl_add_u64 v[8:9], v[12:13], 0, s[40:41]
	s_mov_b32 m0, s56
	s_add_u32 s12, s46, 0x40080
	global_load_lds_dwordx4 v[8:9], off
	v_lshl_add_u64 v[8:9], v[14:15], 0, s[40:41]
	s_mov_b32 m0, s57
	s_addc_u32 s13, s47, 0
	global_load_lds_dwordx4 v[8:9], off
	s_add_i32 m0, s50, 0x1c000
	v_lshl_add_u64 v[8:9], s[12:13], 0, v[134:135]
	global_load_lds_dwordx4 v[8:9], off
	v_lshl_add_u64 v[8:9], s[12:13], 0, v[130:131]
	s_add_i32 m0, s50, 0x1e000
	v_bfe_u32 v142, v0, 4, 2
	global_load_lds_dwordx4 v[8:9], off
	v_and_b32_e32 v81, 15, v0
	v_lshlrev_b32_e32 v7, 4, v142
	v_lshlrev_b32_e32 v0, 2, v0
	v_lshl_or_b32 v7, v81, 6, v7
	v_and_b32_e32 v0, 32, v0
	v_bitop3_b32 v8, v7, s14, v0 bitop3:0xde
	v_bitop3_b32 v143, v7, s5, v0 bitop3:0xde
	v_lshlrev_b32_e32 v0, 14, v5
	v_and_b32_e32 v0, 0xffff8000, v0
	v_lshl_add_u32 v0, v4, 11, v0
	v_and_b32_e32 v4, 1, v5
	v_lshl_or_b32 v0, v4, 6, v0
	v_lshl_add_u32 v138, v6, 1, v0
	v_lshlrev_b32_e32 v0, 14, v1
	v_and_b32_e32 v0, 0xffff8000, v0
	s_waitcnt vmcnt(6)
	v_lshl_add_u32 v0, v2, 11, v0
	v_and_b32_e32 v1, 1, v1
	s_cmpk_lt_u32 s4, 0x100
	v_lshl_or_b32 v0, v1, 6, v0
	v_readlane_b32 s4, v249, 51
	s_cselect_b64 s[12:13], -1, 0
	v_mov_b32_e32 v139, v80
	v_lshl_add_u32 v140, v3, 1, v0
	v_mov_b32_e32 v141, v80
	s_mov_b32 s58, 0
	s_mov_b32 s59, -1
	v_add_u32_e32 v144, 0, v8
	v_readlane_b32 s60, v249, 48
	s_mov_b32 s61, s4
	s_barrier
	v_readlane_b32 s5, v249, 52
	s_branch .LBB0_107

; #define PG8_STAGE(bufoff, gbase, voff) do { _Pragma("unroll") for (int _i = 0; _i < 2; ++_i) \
;         __builtin_amdgcn_global_load_lds((const unsigned*)((const char*)(gbase) + (voff)[_i]), (PG8_LAS unsigned*)(lds + (bufoff) + ldsw + _i * 8192), 16, 0, 0); } while (0)
; #define PG8_LDA(dst, b, h) do { _Pragma("unroll") for (int m = 0; m < 4; ++m) _Pragma("unroll") for (int k = 0; k < 2; ++k) dst[m][k] = *(const PG8_LAS bf16x8*)(lds + PG8_SA(b, h) + aoff + m * 2048 + k * 1024); } while (0)
; #define PG8_LDB(dst, b, h) do { _Pragma("unroll") for (int n = 0; n < 2; ++n) _Pragma("unroll") for (int k = 0; k < 2; ++k) dst[n][k] = *(const PG8_LAS bf16x8*)(lds + PG8_SB(b, h) + boff + n * 2048 + k * 1024); } while (0)
; #define PG8_MMA(ai, bj, At, Bt) do { __builtin_amdgcn_s_setprio(1); _Pragma("unroll") for (int m = 0; m < 4; ++m) _Pragma("unroll") for (int n = 0; n < 2; ++n) _Pragma("unroll") for (int k = 0; k < 2; ++k) \
;         acc[ai][bj][m][n] = __builtin_amdgcn_mfma_f32_16x16x32_bf16(Bt[n][k], At[m][k], acc[ai][bj][m][n], 0, 0, 0); __builtin_amdgcn_s_setprio(0); } while (0)
; #define PG8_WAIT_V(n) asm volatile("s_waitcnt vmcnt(" #n ")" ::: "memory")
; #define PG8_WAIT_L(n) asm volatile("s_waitcnt lgkmcnt(" #n ")" ::: "memory")
; #define PG8_BAR __builtin_amdgcn_s_barrier()
; #define PG8_SCHED __builtin_amdgcn_sched_barrier(0)
; template <class Epi, class Sched, bool ALIGN_EPI = false, bool SP2 = false>
; __device__ __forceinline__ void gemm_phase(PG8_LAS unsigned char* lds, const Gemm g, const Sched& S, const Epi& E) {
;     ...
;             PG8_LDB(B0, 0, 0); PG8_LDB(B1, 0, 1); PG8_SCHED; PG8_LDA(At, 0, 0); PG8_STAGE(PG8_SA(1, 1), a1 + hstep, voffA);
;             PG8_WAIT_V(8); PG8_WAIT_L(0); PG8_BAR; PG8_MMA(0, 0, At, B0); PG8_MMA(0, 1, At, B1); PG8_BAR; PG8_SCHED;
;             PG8_LDA(At, 0, 1); PG8_STAGE(PG8_SB(0, 0), b2, voffB); PG8_STAGE(PG8_SB(0, 1), b2 + hstep, voffB); PG8_STAGE(PG8_SA(0, 0), a2, voffA);
.LBB0_110:
	s_add_u32 s46, s44, 0xfffc0080
	s_addc_u32 s47, s45, -1
	s_add_i32 s67, 0, 0x10000
	s_cmp_eq_u32 s66, 12
	s_cselect_b32 s49, s17, s47
	s_cselect_b32 s48, s62, s46
	v_add_u32_e32 v145, s67, v143
	s_cselect_b32 s47, s15, s65
	s_cselect_b32 s46, s63, s64
	s_add_i32 s70, 0, 0x14000
	ds_read_b128 v[146:149], v145
	ds_read_b128 v[150:153], v145 offset:1024
	ds_read_b128 v[154:157], v145 offset:2048
	ds_read_b128 v[158:161], v145 offset:3072
	v_add_u32_e32 v145, s70, v143
	ds_read_b128 v[176:179], v145
	ds_read_b128 v[180:183], v145 offset:1024
	ds_read_b128 v[184:187], v145 offset:2048
	ds_read_b128 v[188:191], v145 offset:3072
	v_lshl_add_u64 v[200:201], s[44:45], 0, v[138:139]
	s_add_i32 m0, s50, 0xc000
	ds_read_b128 v[192:195], v144
	ds_read_b128 v[196:199], v144 offset:1024
	ds_read_b128 v[208:211], v144 offset:2048
	ds_read_b128 v[212:215], v144 offset:3072
	ds_read_b128 v[216:219], v144 offset:4096
	ds_read_b128 v[220:223], v144 offset:5120
	ds_read_b128 v[224:227], v144 offset:6144
	ds_read_b128 v[228:231], v144 offset:7168
	global_load_lds_dwordx4 v[200:201], off
	v_lshl_add_u64 v[200:201], s[44:45], 0, v[140:141]
	s_add_i32 m0, s50, 0xe000
	s_nop 0
	global_load_lds_dwordx4 v[200:201], off
	s_waitcnt vmcnt(8)
	s_waitcnt lgkmcnt(0)
	s_barrier
	s_setprio 1
	s_waitcnt lgkmcnt(0)
	v_mfma_f32_16x16x32_bf16 v[126:129], v[146:149], v[192:195], v[126:129]
	v_mfma_f32_16x16x32_bf16 v[118:121], v[154:157], v[192:195], v[118:121]
	v_mfma_f32_16x16x32_bf16 v[110:113], v[146:149], v[208:211], v[110:113]
	v_mfma_f32_16x16x32_bf16 v[102:105], v[154:157], v[208:211], v[102:105]
	v_mfma_f32_16x16x32_bf16 v[94:97], v[146:149], v[216:219], v[94:97]
	v_mfma_f32_16x16x32_bf16 v[86:89], v[154:157], v[216:219], v[86:89]
	v_mfma_f32_16x16x32_bf16 v[76:79], v[146:149], v[224:227], v[76:79]
	v_mfma_f32_16x16x32_bf16 v[68:71], v[154:157], v[224:227], v[68:71]
	v_mfma_f32_16x16x32_bf16 v[126:129], v[150:153], v[196:199], v[126:129]
	v_mfma_f32_16x16x32_bf16 v[118:121], v[158:161], v[196:199], v[118:121]
	v_mfma_f32_16x16x32_bf16 v[110:113], v[150:153], v[212:215], v[110:113]
	v_mfma_f32_16x16x32_bf16 v[102:105], v[158:161], v[212:215], v[102:105]
	v_mfma_f32_16x16x32_bf16 v[94:97], v[150:153], v[220:223], v[94:97]
	v_mfma_f32_16x16x32_bf16 v[86:89], v[158:161], v[220:223], v[86:89]
	v_mfma_f32_16x16x32_bf16 v[76:79], v[150:153], v[228:231], v[76:79]
	v_mfma_f32_16x16x32_bf16 v[68:71], v[158:161], v[228:231], v[68:71]
	s_setprio 0
	s_setprio 1
	v_mfma_f32_16x16x32_bf16 v[122:125], v[176:179], v[192:195], v[122:125]
	v_mfma_f32_16x16x32_bf16 v[114:117], v[184:187], v[192:195], v[114:117]
	v_mfma_f32_16x16x32_bf16 v[106:109], v[176:179], v[208:211], v[106:109]
	v_mfma_f32_16x16x32_bf16 v[98:101], v[184:187], v[208:211], v[98:101]
	v_mfma_f32_16x16x32_bf16 v[90:93], v[176:179], v[216:219], v[90:93]
	v_mfma_f32_16x16x32_bf16 v[82:85], v[184:187], v[216:219], v[82:85]
	v_mfma_f32_16x16x32_bf16 v[72:75], v[176:179], v[224:227], v[72:75]
	v_mfma_f32_16x16x32_bf16 v[64:67], v[184:187], v[224:227], v[64:67]
	v_mfma_f32_16x16x32_bf16 v[122:125], v[180:183], v[196:199], v[122:125]
	v_mfma_f32_16x16x32_bf16 v[114:117], v[188:191], v[196:199], v[114:117]
	v_mfma_f32_16x16x32_bf16 v[106:109], v[180:183], v[212:215], v[106:109]
	v_mfma_f32_16x16x32_bf16 v[98:101], v[188:191], v[212:215], v[98:101]
	v_mfma_f32_16x16x32_bf16 v[90:93], v[180:183], v[220:223], v[90:93]
	v_mfma_f32_16x16x32_bf16 v[82:85], v[188:191], v[220:223], v[82:85]
	v_mfma_f32_16x16x32_bf16 v[72:75], v[180:183], v[228:231], v[72:75]
	v_mfma_f32_16x16x32_bf16 v[64:67], v[188:191], v[228:231], v[64:67]
	s_setprio 0
	s_barrier
	s_add_i32 s67, s67, s39
	v_lshl_add_u64 v[200:201], s[46:47], 0, v[134:135]
	s_mov_b32 m0, s67
	ds_read_b128 v[192:195], v144 offset:16384
	ds_read_b128 v[196:199], v144 offset:17408
	ds_read_b128 v[208:211], v144 offset:18432
	ds_read_b128 v[212:215], v144 offset:19456
	ds_read_b128 v[216:219], v144 offset:20480
	ds_read_b128 v[220:223], v144 offset:21504
	ds_read_b128 v[224:227], v144 offset:22528
	ds_read_b128 v[228:231], v144 offset:23552
	global_load_lds_dwordx4 v[200:201], off
	s_add_i32 m0, s67, 0x2000
	s_add_u32 s68, s46, 0x40000
	v_lshl_add_u64 v[232:233], s[46:47], 0, v[130:131]
	s_addc_u32 s69, s47, 0
	s_add_i32 s67, s70, s39
	global_load_lds_dwordx4 v[232:233], off
	v_lshl_add_u64 v[234:235], s[68:69], 0, v[134:135]
	s_mov_b32 m0, s67
	v_lshl_add_u64 v[236:237], s[48:49], 0, v[132:133]
	global_load_lds_dwordx4 v[234:235], off
	v_lshl_add_u64 v[234:235], s[68:69], 0, v[130:131]
	s_add_i32 m0, s67, 0x2000
	s_nop 0
	global_load_lds_dwordx4 v[234:235], off
	v_lshl_add_u64 v[234:235], s[48:49], 0, v[136:137]
	s_mov_b32 m0, s50
	s_nop 0
	global_load_lds_dwordx4 v[234:235], off
	s_mov_b32 m0, s51
	s_nop 0
	global_load_lds_dwordx4 v[236:237], off
	s_waitcnt vmcnt(8)
	s_waitcnt lgkmcnt(0)
	s_barrier
; #define PG8_STAGE(bufoff, gbase, voff) do { _Pragma("unroll") for (int _i = 0; _i < 2; ++_i) \
;         __builtin_amdgcn_global_load_lds((const unsigned*)((const char*)(gbase) + (voff)[_i]), (PG8_LAS unsigned*)(lds + (bufoff) + ldsw + _i * 8192), 16, 0, 0); } while (0)
; #define PG8_LDA(dst, b, h) do { _Pragma("unroll") for (int m = 0; m < 4; ++m) _Pragma("unroll") for (int k = 0; k < 2; ++k) dst[m][k] = *(const PG8_LAS bf16x8*)(lds + PG8_SA(b, h) + aoff + m * 2048 + k * 1024); } while (0)
; #define PG8_LDB(dst, b, h) do { _Pragma("unroll") for (int n = 0; n < 2; ++n) _Pragma("unroll") for (int k = 0; k < 2; ++k) dst[n][k] = *(const PG8_LAS bf16x8*)(lds + PG8_SB(b, h) + boff + n * 2048 + k * 1024); } while (0)
; #define PG8_MMA(ai, bj, At, Bt) do { __builtin_amdgcn_s_setprio(1); _Pragma("unroll") for (int m = 0; m < 4; ++m) _Pragma("unroll") for (int n = 0; n < 2; ++n) _Pragma("unroll") for (int k = 0; k < 2; ++k) \
;         acc[ai][bj][m][n] = __builtin_amdgcn_mfma_f32_16x16x32_bf16(Bt[n][k], At[m][k], acc[ai][bj][m][n], 0, 0, 0); __builtin_amdgcn_s_setprio(0); } while (0)
; #define PG8_WAIT_V(n) asm volatile("s_waitcnt vmcnt(" #n ")" ::: "memory")
; #define PG8_WAIT_L(n) asm volatile("s_waitcnt lgkmcnt(" #n ")" ::: "memory")
; #define PG8_BAR __builtin_amdgcn_s_barrier()
; #define PG8_SCHED __builtin_amdgcn_sched_barrier(0)
; template <class Epi, class Sched, bool ALIGN_EPI = false, bool SP2 = false>
; __device__ __forceinline__ void gemm_phase(PG8_LAS unsigned char* lds, const Gemm g, const Sched& S, const Epi& E) {
;     ...
;             PG8_LDA(At, 0, 1); PG8_STAGE(PG8_SB(0, 0), b2, voffB); PG8_STAGE(PG8_SB(0, 1), b2 + hstep, voffB); PG8_STAGE(PG8_SA(0, 0), a2, voffA);
;             PG8_WAIT_V(8); PG8_WAIT_L(0); PG8_BAR; PG8_MMA(1, 0, At, B0); PG8_MMA(1, 1, At, B1); PG8_BAR; PG8_SCHED;
;             PG8_LDB(B0, 1, 0); PG8_LDB(B1, 1, 1); PG8_SCHED; PG8_LDA(At, 1, 0); PG8_STAGE(PG8_SA(0, 1), a2 + hstep, voffA);
;             PG8_WAIT_V(8); PG8_WAIT_L(0); PG8_BAR; PG8_MMA(0, 0, At, B0); PG8_MMA(0, 1, At, B1); PG8_BAR; PG8_SCHED;
	s_setprio 1
	s_waitcnt lgkmcnt(0)
	v_mfma_f32_16x16x32_bf16 v[60:63], v[146:149], v[192:195], v[60:63]
	v_mfma_f32_16x16x32_bf16 v[52:55], v[154:157], v[192:195], v[52:55]
	v_mfma_f32_16x16x32_bf16 v[44:47], v[146:149], v[208:211], v[44:47]
	v_mfma_f32_16x16x32_bf16 v[36:39], v[154:157], v[208:211], v[36:39]
	v_mfma_f32_16x16x32_bf16 v[28:31], v[146:149], v[216:219], v[28:31]
	v_mfma_f32_16x16x32_bf16 v[20:23], v[154:157], v[216:219], v[20:23]
	v_mfma_f32_16x16x32_bf16 v[12:15], v[146:149], v[224:227], v[12:15]
	v_mfma_f32_16x16x32_bf16 v[4:7], v[154:157], v[224:227], v[4:7]
	v_mfma_f32_16x16x32_bf16 v[60:63], v[150:153], v[196:199], v[60:63]
	v_mfma_f32_16x16x32_bf16 v[52:55], v[158:161], v[196:199], v[52:55]
	v_mfma_f32_16x16x32_bf16 v[44:47], v[150:153], v[212:215], v[44:47]
	v_mfma_f32_16x16x32_bf16 v[36:39], v[158:161], v[212:215], v[36:39]
	v_mfma_f32_16x16x32_bf16 v[28:31], v[150:153], v[220:223], v[28:31]
	v_mfma_f32_16x16x32_bf16 v[20:23], v[158:161], v[220:223], v[20:23]
	v_mfma_f32_16x16x32_bf16 v[12:15], v[150:153], v[228:231], v[12:15]
	v_mfma_f32_16x16x32_bf16 v[4:7], v[158:161], v[228:231], v[4:7]
	s_setprio 0
	s_setprio 1
	v_mfma_f32_16x16x32_bf16 v[56:59], v[176:179], v[192:195], v[56:59]
	v_mfma_f32_16x16x32_bf16 v[48:51], v[184:187], v[192:195], v[48:51]
	v_mfma_f32_16x16x32_bf16 v[40:43], v[176:179], v[208:211], v[40:43]
	v_mfma_f32_16x16x32_bf16 v[32:35], v[184:187], v[208:211], v[32:35]
	v_mfma_f32_16x16x32_bf16 v[24:27], v[176:179], v[216:219], v[24:27]
	v_mfma_f32_16x16x32_bf16 v[16:19], v[184:187], v[216:219], v[16:19]
	v_mfma_f32_16x16x32_bf16 v[8:11], v[176:179], v[224:227], v[8:11]
	v_mfma_f32_16x16x32_bf16 v[0:3], v[184:187], v[224:227], v[0:3]
	v_mfma_f32_16x16x32_bf16 v[56:59], v[180:183], v[196:199], v[56:59]
	v_mfma_f32_16x16x32_bf16 v[48:51], v[188:191], v[196:199], v[48:51]
	v_mfma_f32_16x16x32_bf16 v[40:43], v[180:183], v[212:215], v[40:43]
	v_mfma_f32_16x16x32_bf16 v[32:35], v[188:191], v[212:215], v[32:35]
	v_mfma_f32_16x16x32_bf16 v[24:27], v[180:183], v[220:223], v[24:27]
	v_mfma_f32_16x16x32_bf16 v[16:19], v[188:191], v[220:223], v[16:19]
	v_mfma_f32_16x16x32_bf16 v[8:11], v[180:183], v[228:231], v[8:11]
	v_mfma_f32_16x16x32_bf16 v[0:3], v[188:191], v[228:231], v[0:3]
	s_setprio 0
	s_barrier
	s_add_i32 s67, 0, 0x18000
	v_add_u32_e32 v145, s67, v143
	s_add_i32 s68, 0, 0x1c000
	ds_read_b128 v[146:149], v145
	ds_read_b128 v[150:153], v145 offset:1024
	ds_read_b128 v[154:157], v145 offset:2048
	ds_read_b128 v[158:161], v145 offset:3072
	v_add_u32_e32 v145, s68, v143
	ds_read_b128 v[176:179], v145
	ds_read_b128 v[180:183], v145 offset:1024
	ds_read_b128 v[184:187], v145 offset:2048
	ds_read_b128 v[188:191], v145 offset:3072
	s_add_u32 s48, s48, 0x40000
	s_addc_u32 s49, s49, 0
	s_mov_b32 m0, s52
	v_lshl_add_u64 v[238:239], s[48:49], 0, v[136:137]
	ds_read_b128 v[192:195], v144 offset:32768
	ds_read_b128 v[196:199], v144 offset:33792
	ds_read_b128 v[208:211], v144 offset:34816
	ds_read_b128 v[212:215], v144 offset:35840
	ds_read_b128 v[216:219], v144 offset:36864
	ds_read_b128 v[220:223], v144 offset:37888
	ds_read_b128 v[224:227], v144 offset:38912
	ds_read_b128 v[228:231], v144 offset:39936
	global_load_lds_dwordx4 v[238:239], off
	v_lshl_add_u64 v[238:239], s[48:49], 0, v[132:133]
	s_mov_b32 m0, s53
	s_nop 0
	global_load_lds_dwordx4 v[238:239], off
	s_waitcnt vmcnt(8)
	s_waitcnt lgkmcnt(0)
	s_barrier
	s_setprio 1
	s_waitcnt lgkmcnt(0)
	v_mfma_f32_16x16x32_bf16 v[126:129], v[146:149], v[192:195], v[126:129]
	v_mfma_f32_16x16x32_bf16 v[118:121], v[154:157], v[192:195], v[118:121]
	v_mfma_f32_16x16x32_bf16 v[110:113], v[146:149], v[208:211], v[110:113]
	v_mfma_f32_16x16x32_bf16 v[102:105], v[154:157], v[208:211], v[102:105]
	v_mfma_f32_16x16x32_bf16 v[94:97], v[146:149], v[216:219], v[94:97]
	v_mfma_f32_16x16x32_bf16 v[86:89], v[154:157], v[216:219], v[86:89]
	v_mfma_f32_16x16x32_bf16 v[76:79], v[146:149], v[224:227], v[76:79]
	v_mfma_f32_16x16x32_bf16 v[68:71], v[154:157], v[224:227], v[68:71]
	v_mfma_f32_16x16x32_bf16 v[126:129], v[150:153], v[196:199], v[126:129]
	v_mfma_f32_16x16x32_bf16 v[118:121], v[158:161], v[196:199], v[118:121]
	v_mfma_f32_16x16x32_bf16 v[110:113], v[150:153], v[212:215], v[110:113]
	v_mfma_f32_16x16x32_bf16 v[102:105], v[158:161], v[212:215], v[102:105]
	v_mfma_f32_16x16x32_bf16 v[94:97], v[150:153], v[220:223], v[94:97]
	v_mfma_f32_16x16x32_bf16 v[86:89], v[158:161], v[220:223], v[86:89]
	v_mfma_f32_16x16x32_bf16 v[76:79], v[150:153], v[228:231], v[76:79]
	v_mfma_f32_16x16x32_bf16 v[68:71], v[158:161], v[228:231], v[68:71]
	s_setprio 0
	s_setprio 1
	v_mfma_f32_16x16x32_bf16 v[122:125], v[176:179], v[192:195], v[122:125]
	v_mfma_f32_16x16x32_bf16 v[114:117], v[184:187], v[192:195], v[114:117]
	v_mfma_f32_16x16x32_bf16 v[106:109], v[176:179], v[208:211], v[106:109]
	v_mfma_f32_16x16x32_bf16 v[98:101], v[184:187], v[208:211], v[98:101]
	v_mfma_f32_16x16x32_bf16 v[90:93], v[176:179], v[216:219], v[90:93]
	v_mfma_f32_16x16x32_bf16 v[82:85], v[184:187], v[216:219], v[82:85]
	v_mfma_f32_16x16x32_bf16 v[72:75], v[176:179], v[224:227], v[72:75]
	v_mfma_f32_16x16x32_bf16 v[64:67], v[184:187], v[224:227], v[64:67]
	v_mfma_f32_16x16x32_bf16 v[122:125], v[180:183], v[196:199], v[122:125]
	v_mfma_f32_16x16x32_bf16 v[114:117], v[188:191], v[196:199], v[114:117]
	v_mfma_f32_16x16x32_bf16 v[106:109], v[180:183], v[212:215], v[106:109]
	v_mfma_f32_16x16x32_bf16 v[98:101], v[188:191], v[212:215], v[98:101]
	v_mfma_f32_16x16x32_bf16 v[90:93], v[180:183], v[220:223], v[90:93]
	v_mfma_f32_16x16x32_bf16 v[82:85], v[188:191], v[220:223], v[82:85]
	v_mfma_f32_16x16x32_bf16 v[72:75], v[180:183], v[228:231], v[72:75]
	v_mfma_f32_16x16x32_bf16 v[64:67], v[188:191], v[228:231], v[64:67]
	s_setprio 0
	s_barrier
; #define PG8_STAGE(bufoff, gbase, voff) do { _Pragma("unroll") for (int _i = 0; _i < 2; ++_i) \
;         __builtin_amdgcn_global_load_lds((const unsigned*)((const char*)(gbase) + (voff)[_i]), (PG8_LAS unsigned*)(lds + (bufoff) + ldsw + _i * 8192), 16, 0, 0); } while (0)
; #define PG8_LDA(dst, b, h) do { _Pragma("unroll") for (int m = 0; m < 4; ++m) _Pragma("unroll") for (int k = 0; k < 2; ++k) dst[m][k] = *(const PG8_LAS bf16x8*)(lds + PG8_SA(b, h) + aoff + m * 2048 + k * 1024); } while (0)
; #define PG8_MMA(ai, bj, At, Bt) do { __builtin_amdgcn_s_setprio(1); _Pragma("unroll") for (int m = 0; m < 4; ++m) _Pragma("unroll") for (int n = 0; n < 2; ++n) _Pragma("unroll") for (int k = 0; k < 2; ++k) \
;         acc[ai][bj][m][n] = __builtin_amdgcn_mfma_f32_16x16x32_bf16(Bt[n][k], At[m][k], acc[ai][bj][m][n], 0, 0, 0); __builtin_amdgcn_s_setprio(0); } while (0)
; #define PG8_WAIT_V(n) asm volatile("s_waitcnt vmcnt(" #n ")" ::: "memory")
; #define PG8_WAIT_L(n) asm volatile("s_waitcnt lgkmcnt(" #n ")" ::: "memory")
; #define PG8_BAR __builtin_amdgcn_s_barrier()
; #define PG8_SCHED __builtin_amdgcn_sched_barrier(0)
; template <class Epi, class Sched, bool ALIGN_EPI = false, bool SP2 = false>
; __device__ __forceinline__ void gemm_phase(PG8_LAS unsigned char* lds, const Gemm g, const Sched& S, const Epi& E) {
;     ...
;         for (int t = 0; t < nt; t += 2) {
;             if constexpr (Epi::PF_TRIPS > 0) { if (t == nt - 2 * Epi::PF_TRIPS) E.prefetch(cur, tid, lds + STAGE_BYTES + wid * 512); }
;             const bool last = (t == nt - 2);
;             const char* a1 = cA + (size_t)(t + 1) * kstep;
;             const char* a2 = last ? nA : cA + (size_t)(t + 2) * kstep; const char* b2 = last ? nB : cB + (size_t)(t + 2) * kstep;
;             const char* a3 = a2 + kstep; const char* b3 = b2 + kstep;
;     ...
;             PG8_LDA(At, 1, 1); PG8_STAGE(PG8_SB(1, 0), b3, voffB); PG8_STAGE(PG8_SB(1, 1), b3 + hstep, voffB); PG8_STAGE(PG8_SA(1, 0), a3, voffA);
;             PG8_WAIT_V(8); PG8_WAIT_L(0); PG8_BAR; PG8_MMA(1, 0, At, B0); PG8_MMA(1, 1, At, B1); PG8_BAR; PG8_SCHED;
	s_add_i32 s48, s67, s39
	v_lshl_add_u64 v[200:201], v[200:201], 0, s[40:41]
	s_mov_b32 m0, s48
	ds_read_b128 v[192:195], v144 offset:49152
	ds_read_b128 v[196:199], v144 offset:50176
	ds_read_b128 v[208:211], v144 offset:51200
	ds_read_b128 v[212:215], v144 offset:52224
	ds_read_b128 v[216:219], v144 offset:53248
	ds_read_b128 v[220:223], v144 offset:54272
	ds_read_b128 v[224:227], v144 offset:55296
	ds_read_b128 v[228:231], v144 offset:56320
	global_load_lds_dwordx4 v[200:201], off
	s_add_i32 m0, s48, 0x2000
	s_add_u32 s46, s46, 0x40080
	v_lshl_add_u64 v[200:201], v[232:233], 0, s[40:41]
	s_addc_u32 s47, s47, 0
	s_add_i32 s48, s68, s39
	global_load_lds_dwordx4 v[200:201], off
	v_lshl_add_u64 v[200:201], s[46:47], 0, v[134:135]
	s_mov_b32 m0, s48
	s_nop 0
	global_load_lds_dwordx4 v[200:201], off
	v_lshl_add_u64 v[200:201], s[46:47], 0, v[130:131]
	s_add_i32 m0, s48, 0x2000
	s_nop 0
	global_load_lds_dwordx4 v[200:201], off
	v_lshl_add_u64 v[200:201], v[234:235], 0, s[40:41]
	s_mov_b32 m0, s56
	s_nop 0
	global_load_lds_dwordx4 v[200:201], off
	v_lshl_add_u64 v[200:201], v[236:237], 0, s[40:41]
	s_mov_b32 m0, s57
	s_nop 0
	global_load_lds_dwordx4 v[200:201], off
	s_waitcnt vmcnt(8)
	s_waitcnt lgkmcnt(0)
	s_barrier
	s_setprio 1
	s_waitcnt lgkmcnt(0)
	v_mfma_f32_16x16x32_bf16 v[60:63], v[146:149], v[192:195], v[60:63]
	v_mfma_f32_16x16x32_bf16 v[52:55], v[154:157], v[192:195], v[52:55]
	v_mfma_f32_16x16x32_bf16 v[44:47], v[146:149], v[208:211], v[44:47]
	v_mfma_f32_16x16x32_bf16 v[36:39], v[154:157], v[208:211], v[36:39]
	v_mfma_f32_16x16x32_bf16 v[28:31], v[146:149], v[216:219], v[28:31]
	v_mfma_f32_16x16x32_bf16 v[20:23], v[154:157], v[216:219], v[20:23]
	v_mfma_f32_16x16x32_bf16 v[12:15], v[146:149], v[224:227], v[12:15]
	v_mfma_f32_16x16x32_bf16 v[4:7], v[154:157], v[224:227], v[4:7]
	v_mfma_f32_16x16x32_bf16 v[60:63], v[150:153], v[196:199], v[60:63]
	v_mfma_f32_16x16x32_bf16 v[52:55], v[158:161], v[196:199], v[52:55]
	v_mfma_f32_16x16x32_bf16 v[44:47], v[150:153], v[212:215], v[44:47]
	v_mfma_f32_16x16x32_bf16 v[36:39], v[158:161], v[212:215], v[36:39]
	v_mfma_f32_16x16x32_bf16 v[28:31], v[150:153], v[220:223], v[28:31]
	v_mfma_f32_16x16x32_bf16 v[20:23], v[158:161], v[220:223], v[20:23]
	v_mfma_f32_16x16x32_bf16 v[12:15], v[150:153], v[228:231], v[12:15]
	v_mfma_f32_16x16x32_bf16 v[4:7], v[158:161], v[228:231], v[4:7]
	s_setprio 0
	s_setprio 1
	v_mfma_f32_16x16x32_bf16 v[56:59], v[176:179], v[192:195], v[56:59]
	v_mfma_f32_16x16x32_bf16 v[48:51], v[184:187], v[192:195], v[48:51]
	v_mfma_f32_16x16x32_bf16 v[40:43], v[176:179], v[208:211], v[40:43]
	v_mfma_f32_16x16x32_bf16 v[32:35], v[184:187], v[208:211], v[32:35]
	v_mfma_f32_16x16x32_bf16 v[24:27], v[176:179], v[216:219], v[24:27]
	v_mfma_f32_16x16x32_bf16 v[16:19], v[184:187], v[216:219], v[16:19]
	v_mfma_f32_16x16x32_bf16 v[8:11], v[176:179], v[224:227], v[8:11]
	v_mfma_f32_16x16x32_bf16 v[0:3], v[184:187], v[224:227], v[0:3]
	v_mfma_f32_16x16x32_bf16 v[56:59], v[180:183], v[196:199], v[56:59]
	v_mfma_f32_16x16x32_bf16 v[48:51], v[188:191], v[196:199], v[48:51]
	v_mfma_f32_16x16x32_bf16 v[40:43], v[180:183], v[212:215], v[40:43]
	v_mfma_f32_16x16x32_bf16 v[32:35], v[188:191], v[212:215], v[32:35]
	v_mfma_f32_16x16x32_bf16 v[24:27], v[180:183], v[220:223], v[24:27]
	v_mfma_f32_16x16x32_bf16 v[16:19], v[188:191], v[220:223], v[16:19]
	v_mfma_f32_16x16x32_bf16 v[8:11], v[180:183], v[228:231], v[8:11]
	v_mfma_f32_16x16x32_bf16 v[0:3], v[188:191], v[228:231], v[0:3]
	s_setprio 0
	s_barrier
	s_add_i32 s66, s66, 2
	s_add_u32 s44, s44, 0x100
	s_addc_u32 s45, s45, 0
	s_add_u32 s64, s64, 0x100
	s_addc_u32 s65, s65, 0
	s_cmp_gt_u32 s66, 13
	s_cbranch_scc0 .LBB0_110
	s_and_b64 vcc, exec, s[12:13]
	s_cbranch_vccz .LBB0_113
	s_barrier

; __global__ void __launch_bounds__(NTHREADS, 2) fwd_megakernel(Params P) {
	.amdhsa_kernel _Z14fwd_megakernel6Params
		.amdhsa_group_segment_fixed_size 0
		.amdhsa_private_segment_fixed_size 0
		.amdhsa_kernarg_size 400
		.amdhsa_user_sgpr_count 2
		.amdhsa_user_sgpr_dispatch_ptr 0
		.amdhsa_user_sgpr_queue_ptr 0
		.amdhsa_user_sgpr_kernarg_segment_ptr 1
		.amdhsa_user_sgpr_dispatch_id 0
		.amdhsa_user_sgpr_kernarg_preload_length 0
		.amdhsa_user_sgpr_kernarg_preload_offset 0
		.amdhsa_user_sgpr_private_segment_size 0
		.amdhsa_uses_dynamic_stack 0
		.amdhsa_enable_private_segment 0
		.amdhsa_system_sgpr_workgroup_id_x 1
		.amdhsa_system_sgpr_workgroup_id_y 0
		.amdhsa_system_sgpr_workgroup_id_z 0
		.amdhsa_system_sgpr_workgroup_info 0
		.amdhsa_system_vgpr_workitem_id 2
		.amdhsa_next_free_vgpr 251
		.amdhsa_next_free_sgpr 100
		.amdhsa_accum_offset 252
		.amdhsa_reserve_vcc 1
		.amdhsa_float_round_mode_32 0
		.amdhsa_float_round_mode_16_64 0
		.amdhsa_float_denorm_mode_32 3
		.amdhsa_float_denorm_mode_16_64 3
		.amdhsa_dx10_clamp 1
		.amdhsa_ieee_mode 1
		.amdhsa_fp16_overflow 0
		.amdhsa_tg_split 0
		.amdhsa_exception_fp_ieee_invalid_op 0
		.amdhsa_exception_fp_denorm_src 0
		.amdhsa_exception_fp_ieee_div_zero 0
		.amdhsa_exception_fp_ieee_overflow 0
		.amdhsa_exception_fp_ieee_underflow 0
		.amdhsa_exception_fp_ieee_inexact 0
		.amdhsa_exception_int_div_zero 0
	.end_amdhsa_kernel

; __global__ void __launch_bounds__(NTHREADS, 2) fwd_megakernel(Params P) {
amdhsa.kernels:
  - .agpr_count:     0
    .args:
      - .offset:         0
        .size:           144
        .value_kind:     by_value
      - .offset:         144
        .size:           4
        .value_kind:     hidden_block_count_x
      - .offset:         148
        .size:           4
        .value_kind:     hidden_block_count_y
      - .offset:         152
        .size:           4
        .value_kind:     hidden_block_count_z
      - .offset:         156
        .size:           2
        .value_kind:     hidden_group_size_x
      - .offset:         158
        .size:           2
        .value_kind:     hidden_group_size_y
      - .offset:         160
        .size:           2
        .value_kind:     hidden_group_size_z
      - .offset:         162
        .size:           2
        .value_kind:     hidden_remainder_x
      - .offset:         164
        .size:           2
        .value_kind:     hidden_remainder_y
      - .offset:         166
        .size:           2
        .value_kind:     hidden_remainder_z
      - .offset:         184
        .size:           8
        .value_kind:     hidden_global_offset_x
      - .offset:         192
        .size:           8
        .value_kind:     hidden_global_offset_y
      - .offset:         200
        .size:           8
        .value_kind:     hidden_global_offset_z
      - .offset:         208
        .size:           2
        .value_kind:     hidden_grid_dims
      - .offset:         232
        .size:           8
        .value_kind:     hidden_multigrid_sync_arg
      - .offset:         264
        .size:           4
        .value_kind:     hidden_dynamic_lds_size
    .group_segment_fixed_size: 0
    .kernarg_segment_align: 8
    .kernarg_segment_size: 400
    .language:       OpenCL C
    .language_version:
      - 2
      - 0
    .max_flat_workgroup_size: 512
    .name:           _Z14fwd_megakernel6Params
    .private_segment_fixed_size: 0
    .sgpr_count:     106
    .sgpr_spill_count: 188
    .symbol:         _Z14fwd_megakernel6Params.kd
    .uniform_work_group_size: 1
    .uses_dynamic_stack: false
    .vgpr_count:     251
    .vgpr_spill_count: 0
    .wavefront_size: 64
